# P4/P6 small-M path: reduction ds_reads issued back to back, second residual load hoisted next to the first; on top of v31
# speedup vs baseline: 1.0104x; 1.0104x over previous
; #define LAS __attribute__((address_space(3)))
; template <int KSTEPS  >
; __device__ __forceinline__ void small_mma_ksplit(f32x4 (&acc)[2], const bf16_t* A, int lda, const bf16_t* Bt, int ldb, int n0, LAS unsigned char* lds, const SmallId& id) {
;     ...
;     for (int ks = 0; ks < KSTEPS; ++ks) {
;         bf16x8 a[8], b[2];
; #pragma unroll
;         for (int rb = 0; rb < 8; ++rb) a[rb] = *(const bf16x8*)(ap + (size_t)(16 * rb) * lda + 32 * ks);
;         b[0] = *(const bf16x8*)(bp + 32 * ks); b[1] = *(const bf16x8*)(bp + (size_t)16 * ldb + 32 * ks);
; #pragma unroll
;         for (int rb = 0; rb < 8; ++rb) { part[rb][0] = __builtin_amdgcn_mfma_f32_16x16x32_bf16(b[0], a[rb], part[rb][0], 0, 0, 0); part[rb][1] = __builtin_amdgcn_mfma_f32_16x16x32_bf16(b[1], a[rb], part[rb][1], 0, 0, 0); }
;     }
;     LAS f32x4* red = (LAS f32x4*)lds;
; #pragma unroll
;     for (int rb = 0; rb < 8; ++rb) { red[((id.w * 8 + rb) * 2 + 0) * 64 + lane] = part[rb][0]; red[((id.w * 8 + rb) * 2 + 1) * 64 + lane] = part[rb][1]; }
;     asm volatile("s_waitcnt lgkmcnt(0)" ::: "memory"); __syncthreads();
;     acc[0] = (f32x4){0.f, 0.f, 0.f, 0.f}; acc[1] = acc[0];
; #pragma unroll
;     for (int w2 = 0; w2 < 8; ++w2) { acc[0] += red[((w2 * 8 + id.w) * 2 + 0) * 64 + lane]; acc[1] += red[((w2 * 8 + id.w) * 2 + 1) * 64 + lane]; }
;     asm volatile("s_waitcnt lgkmcnt(0)" ::: "memory"); __syncthreads();
; template <bool RES_F32, bool OUT_F32, int KSTEPS>
; __device__ __forceinline__ void small_res(const Params& p, LAS unsigned char* lds, const bf16_t* A, int lda, const bf16_t* Bt, int K, float* ssq_next, int G, int bx) {
;     ...
;     for (int ts = G - 1 - bx; ts < DM / 32; ts += G) {
;         const int n0 = ts * 32; f32x4 acc[2] = {(f32x4){0.f, 0.f, 0.f, 0.f}, (f32x4){0.f, 0.f, 0.f, 0.f}};
;         small_mma_ksplit<KSTEPS>(acc, A, lda, Bt, K, n0, lds, id);
;         float s = 0.f;
; #pragma unroll
;         for (int nb = 0; nb < 2; ++nb) { const int col = n0 + 16 * nb + 4 * id.fq;
;             f32x4 r;
;             if (RES_F32) r = *(const f32x4*)(p.xs + (size_t)(id.row - MP) * DM + col);
;             else { const u32x2 w = *(const u32x2*)(XB + (size_t)id.row * DM + col); r = (f32x4){bf_lo(w.x), bf_hi(w.x), bf_lo(w.y), bf_hi(w.y)}; }
;             const f32x4 x = r + acc[nb];
;             if (OUT_F32) *(f32x4*)(p.out + (size_t)id.row * DM + col) = x;
.LBB0_863:
	s_waitcnt lgkmcnt(0)
	v_readlane_b32 s8, v246, 8
	v_readfirstlane_b32 s32, v222
	s_bfe_u32 s8, s8, 0x30003
	s_lshr_b32 s32, s32, 6
	s_cmp_eq_u32 s32, s8
	s_cselect_b32 s32, 1, 0
	s_lshl_b32 s9, s8, 11
	v_add_u32_e32 v68, s9, v76
	s_sub_i32 s9, s11, s10
	s_mul_i32 s8, s8, s9
	s_add_i32 s8, s8, s10
	s_mov_b32 s9, 0
	v_lshl_add_u64 v[70:71], v[72:73], 0, s[8:9]
	s_mov_b32 s8, s18
	v_lshl_add_u64 v[88:89], v[74:75], 0, s[8:9]
	s_mov_b32 s8, s19
	v_lshl_add_u64 v[90:91], v[74:75], 0, s[8:9]
	global_load_dwordx4 v[92:95], v[70:71], off
	global_load_dwordx4 v[98:101], v[88:89], off
	global_load_dwordx4 v[102:105], v[90:91], off
	global_load_dwordx4 v[106:109], v[70:71], off offset:64
	global_load_dwordx4 v[110:113], v[88:89], off offset:64
	global_load_dwordx4 v[114:117], v[90:91], off offset:64
	global_load_dwordx4 v[118:121], v[70:71], off offset:128
	global_load_dwordx4 v[122:125], v[88:89], off offset:128
	global_load_dwordx4 v[126:129], v[90:91], off offset:128
	global_load_dwordx4 v[130:133], v[70:71], off offset:192
	global_load_dwordx4 v[134:137], v[88:89], off offset:192
	global_load_dwordx4 v[138:141], v[90:91], off offset:192
	s_waitcnt vmcnt(9)
	v_mfma_f32_16x16x32_bf16 v[36:39], v[98:101], v[92:95], v[36:39]
	v_mfma_f32_16x16x32_bf16 v[24:27], v[102:105], v[92:95], v[24:27]
	s_waitcnt vmcnt(6)
	v_mfma_f32_16x16x32_bf16 v[36:39], v[110:113], v[106:109], v[36:39]
	v_mfma_f32_16x16x32_bf16 v[24:27], v[114:117], v[106:109], v[24:27]
	s_waitcnt vmcnt(3)
	v_mfma_f32_16x16x32_bf16 v[36:39], v[122:125], v[118:121], v[36:39]
	v_mfma_f32_16x16x32_bf16 v[24:27], v[126:129], v[118:121], v[24:27]
	s_waitcnt vmcnt(0)
	v_mfma_f32_16x16x32_bf16 v[36:39], v[134:137], v[130:133], v[36:39]
	v_mfma_f32_16x16x32_bf16 v[24:27], v[138:141], v[130:133], v[24:27]
	s_nop 7
	s_nop 1
	ds_write_b128 v68, v[36:39]
	ds_write_b128 v68, v[24:27] offset:1024
	s_waitcnt lgkmcnt(0)
	s_waitcnt lgkmcnt(0)
	s_barrier
	ds_read_b128 v[92:95], v77
	ds_read_b128 v[98:101], v77 offset:1024
	ds_read_b128 v[102:105], v77 offset:16384
	ds_read_b128 v[106:109], v77 offset:17408
	ds_read_b128 v[110:113], v77 offset:32768
	ds_read_b128 v[114:117], v77 offset:33792
	ds_read_b128 v[118:121], v77 offset:49152
	ds_read_b128 v[122:125], v77 offset:50176
	ds_read_b128 v[126:129], v78
	ds_read_b128 v[130:133], v79
	ds_read_b128 v[134:137], v80
	ds_read_b128 v[138:141], v81
	ds_read_b128 v[142:145], v82
	ds_read_b128 v[146:149], v83
	ds_read_b128 v[150:153], v84
	ds_read_b128 v[0:3], v85
	s_waitcnt lgkmcnt(0)
	v_pk_add_f32 v[4:5], v[94:95], 0 op_sel_hi:[1,0]
	v_pk_add_f32 v[6:7], v[92:93], 0 op_sel_hi:[1,0]
	v_pk_add_f32 v[8:9], v[100:101], 0 op_sel_hi:[1,0]
	v_pk_add_f32 v[10:11], v[98:99], 0 op_sel_hi:[1,0]
	v_pk_add_f32 v[4:5], v[4:5], v[104:105]
	v_pk_add_f32 v[6:7], v[6:7], v[102:103]
	v_pk_add_f32 v[8:9], v[8:9], v[108:109]
	v_pk_add_f32 v[10:11], v[10:11], v[106:107]
	v_pk_add_f32 v[4:5], v[4:5], v[112:113]
	v_pk_add_f32 v[6:7], v[6:7], v[110:111]
	v_pk_add_f32 v[8:9], v[8:9], v[116:117]
	v_pk_add_f32 v[10:11], v[10:11], v[114:115]
	v_pk_add_f32 v[4:5], v[4:5], v[120:121]
	v_pk_add_f32 v[6:7], v[6:7], v[118:119]
	v_pk_add_f32 v[8:9], v[8:9], v[124:125]
	v_pk_add_f32 v[10:11], v[10:11], v[122:123]
	v_pk_add_f32 v[4:5], v[4:5], v[128:129]
	v_pk_add_f32 v[6:7], v[6:7], v[126:127]
	v_pk_add_f32 v[8:9], v[8:9], v[132:133]
	v_pk_add_f32 v[10:11], v[10:11], v[130:131]
	v_pk_add_f32 v[4:5], v[4:5], v[136:137]
	v_pk_add_f32 v[6:7], v[6:7], v[134:135]
	v_pk_add_f32 v[8:9], v[8:9], v[140:141]
	v_pk_add_f32 v[10:11], v[10:11], v[138:139]
	v_pk_add_f32 v[4:5], v[4:5], v[144:145]
	v_pk_add_f32 v[6:7], v[6:7], v[142:143]
	v_pk_add_f32 v[8:9], v[8:9], v[148:149]
	v_pk_add_f32 v[10:11], v[10:11], v[146:147]
	v_pk_add_f32 v[4:5], v[4:5], v[152:153]
	v_pk_add_f32 v[6:7], v[6:7], v[150:151]
	s_waitcnt lgkmcnt(0)
	s_waitcnt lgkmcnt(0)
	s_barrier
	s_mul_i32 exec_lo, s32, -1
	s_mov_b32 exec_hi, exec_lo
	v_pk_add_f32 v[2:3], v[8:9], v[2:3]
	v_lshl_or_b32 v8, s7, 5, v86
	v_ashrrev_i32_e32 v9, 31, v8
	v_lshl_add_u64 v[8:9], v[8:9], 1, v[64:65]
	v_pk_add_f32 v[0:1], v[10:11], v[0:1]
	global_load_dwordx2 v[10:11], v[8:9], off
	global_load_dwordx2 v[158:159], v[8:9], off offset:32
	s_waitcnt vmcnt(0) lgkmcnt(0)
	v_lshlrev_b32_e32 v12, 16, v10
	v_and_b32_e32 v13, 0xffff0000, v10
	v_lshlrev_b32_e32 v10, 16, v11
	v_and_b32_e32 v11, 0xffff0000, v11
	v_pk_add_f32 v[4:5], v[4:5], v[10:11]
	v_pk_add_f32 v[6:7], v[6:7], v[12:13]
	s_nop 0
	v_cvt_pk_bf16_f32 v10, v6, v7
	v_cvt_pk_bf16_f32 v11, v4, v5
	v_mul_f32_e32 v7, v7, v7
	v_mul_f32_e32 v5, v5, v5
	v_fmac_f32_e32 v7, v6, v6
	v_fmac_f32_e32 v5, v4, v4
	global_store_dwordx2 v[8:9], v[10:11], off
	v_add_f32_e32 v10, v7, v5
	s_waitcnt vmcnt(0) lgkmcnt(0)
	v_lshlrev_b32_e32 v6, 16, v158
	v_and_b32_e32 v7, 0xffff0000, v158
	v_lshlrev_b32_e32 v4, 16, v159
	v_and_b32_e32 v5, 0xffff0000, v159
	v_pk_add_f32 v[0:1], v[0:1], v[6:7]
	v_pk_add_f32 v[2:3], v[2:3], v[4:5]
	v_cvt_pk_bf16_f32 v4, v0, v1
	v_mul_f32_e32 v1, v1, v1
	v_fmac_f32_e32 v1, v0, v0
	v_mul_f32_e32 v0, v3, v3
	v_cvt_pk_bf16_f32 v5, v2, v3
	v_fmac_f32_e32 v0, v2, v2
	v_and_b32_e32 v2, 64, v225
	v_add_f32_e32 v0, v1, v0
	v_xor_b32_e32 v1, 16, v225
	v_add_u32_e32 v2, 64, v2
	v_cmp_lt_i32_e64 s[0:1], v1, v2
	v_add_f32_e32 v0, v10, v0
	global_store_dwordx2 v[8:9], v[4:5], off offset:32
	v_cndmask_b32_e64 v1, v225, v1, s[0:1]
	v_lshlrev_b32_e32 v1, 2, v1
	ds_bpermute_b32 v1, v1, v0
	s_waitcnt lgkmcnt(0)
	v_add_f32_e32 v0, v0, v1
	v_xor_b32_e32 v1, 32, v225
	v_cmp_lt_i32_e64 s[0:1], v1, v2
	s_nop 1
	v_cndmask_b32_e64 v1, v225, v1, s[0:1]
	v_lshlrev_b32_e32 v1, 2, v1
	ds_bpermute_b32 v1, v1, v0
	s_and_saveexec_b64 s[0:1], vcc
	s_cbranch_execz .LBB0_861
	s_waitcnt lgkmcnt(0)
	v_add_f32_e32 v0, v0, v1
	global_atomic_add_f32 v[66:67], v0, off
	s_branch .LBB0_861

; template <int KSTEPS  >
; __device__ __forceinline__ void small_mma_ksplit(f32x4 (&acc)[2], const bf16_t* A, int lda, const bf16_t* Bt, int ldb, int n0, LAS unsigned char* lds, const SmallId& id) {
;     ...
;     for (int ks = 0; ks < KSTEPS; ++ks) {
;         bf16x8 a[8], b[2];
; #pragma unroll
;         for (int rb = 0; rb < 8; ++rb) a[rb] = *(const bf16x8*)(ap + (size_t)(16 * rb) * lda + 32 * ks);
;         b[0] = *(const bf16x8*)(bp + 32 * ks); b[1] = *(const bf16x8*)(bp + (size_t)16 * ldb + 32 * ks);
; #pragma unroll
;         for (int rb = 0; rb < 8; ++rb) { part[rb][0] = __builtin_amdgcn_mfma_f32_16x16x32_bf16(b[0], a[rb], part[rb][0], 0, 0, 0); part[rb][1] = __builtin_amdgcn_mfma_f32_16x16x32_bf16(b[1], a[rb], part[rb][1], 0, 0, 0); }
;     }
;     LAS f32x4* red = (LAS f32x4*)lds;
; #pragma unroll
;     for (int rb = 0; rb < 8; ++rb) { red[((id.w * 8 + rb) * 2 + 0) * 64 + lane] = part[rb][0]; red[((id.w * 8 + rb) * 2 + 1) * 64 + lane] = part[rb][1]; }
;     asm volatile("s_waitcnt lgkmcnt(0)" ::: "memory"); __syncthreads();
;     acc[0] = (f32x4){0.f, 0.f, 0.f, 0.f}; acc[1] = acc[0];
; #pragma unroll
;     for (int w2 = 0; w2 < 8; ++w2) { acc[0] += red[((w2 * 8 + id.w) * 2 + 0) * 64 + lane]; acc[1] += red[((w2 * 8 + id.w) * 2 + 1) * 64 + lane]; }
;     asm volatile("s_waitcnt lgkmcnt(0)" ::: "memory"); __syncthreads();
; template <bool RES_F32, bool OUT_F32, int KSTEPS>
; __device__ __forceinline__ void small_res(const Params& p, LAS unsigned char* lds, const bf16_t* A, int lda, const bf16_t* Bt, int K, float* ssq_next, int G, int bx) {
;     ...
;         for (int nb = 0; nb < 2; ++nb) { const int col = n0 + 16 * nb + 4 * id.fq;
;             f32x4 r;
;             if (RES_F32) r = *(const f32x4*)(p.xs + (size_t)(id.row - MP) * DM + col);
;             else { const u32x2 w = *(const u32x2*)(XB + (size_t)id.row * DM + col); r = (f32x4){bf_lo(w.x), bf_hi(w.x), bf_lo(w.y), bf_hi(w.y)}; }
;             const f32x4 x = r + acc[nb];
;             if (OUT_F32) *(f32x4*)(p.out + (size_t)id.row * DM + col) = x;
;             else { u32x2 w; w.x = cvt_pk_bf16(x[0], x[1]); w.y = cvt_pk_bf16(x[2], x[3]); *(u32x2*)(XB + (size_t)id.row * DM + col) = w; }
;             s += (x[0] * x[0] + x[1] * x[1]) + (x[2] * x[2] + x[3] * x[3]); }
;         if (!OUT_F32) { s += __shfl_xor(s, 16); s += __shfl_xor(s, 32); if (id.fq == 0) atomicAdd(ssq_next + id.row, s); }
.LBB0_908:
	s_waitcnt lgkmcnt(0)
	v_readlane_b32 s8, v246, 8
	v_readfirstlane_b32 s32, v222
	s_bfe_u32 s8, s8, 0x30003
	s_lshr_b32 s32, s32, 6
	s_cmp_eq_u32 s32, s8
	s_cselect_b32 s32, 1, 0
	s_lshl_b32 s9, s8, 11
	v_add_u32_e32 v70, s9, v78
	s_sub_i32 s9, s11, s10
	s_mul_i32 s8, s8, s9
	s_add_i32 s8, s8, s10
	s_mov_b32 s9, 0
	v_lshl_add_u64 v[72:73], v[74:75], 0, s[8:9]
	s_mov_b32 s8, s18
	v_lshl_add_u64 v[90:91], v[76:77], 0, s[8:9]
	s_mov_b32 s8, s19
	v_lshl_add_u64 v[92:93], v[76:77], 0, s[8:9]
	global_load_dwordx4 v[98:101], v[72:73], off
	global_load_dwordx4 v[102:105], v[90:91], off
	global_load_dwordx4 v[106:109], v[92:93], off
	global_load_dwordx4 v[110:113], v[72:73], off offset:64
	global_load_dwordx4 v[114:117], v[90:91], off offset:64
	global_load_dwordx4 v[118:121], v[92:93], off offset:64
	global_load_dwordx4 v[122:125], v[72:73], off offset:128
	global_load_dwordx4 v[126:129], v[90:91], off offset:128
	global_load_dwordx4 v[130:133], v[92:93], off offset:128
	global_load_dwordx4 v[134:137], v[72:73], off offset:192
	global_load_dwordx4 v[138:141], v[90:91], off offset:192
	global_load_dwordx4 v[142:145], v[92:93], off offset:192
	s_waitcnt vmcnt(9)
	v_mfma_f32_16x16x32_bf16 v[36:39], v[102:105], v[98:101], v[36:39]
	v_mfma_f32_16x16x32_bf16 v[24:27], v[106:109], v[98:101], v[24:27]
	s_waitcnt vmcnt(6)
	v_mfma_f32_16x16x32_bf16 v[36:39], v[114:117], v[110:113], v[36:39]
	v_mfma_f32_16x16x32_bf16 v[24:27], v[118:121], v[110:113], v[24:27]
	s_waitcnt vmcnt(3)
	v_mfma_f32_16x16x32_bf16 v[36:39], v[126:129], v[122:125], v[36:39]
	v_mfma_f32_16x16x32_bf16 v[24:27], v[130:133], v[122:125], v[24:27]
	s_waitcnt vmcnt(0)
	v_mfma_f32_16x16x32_bf16 v[36:39], v[138:141], v[134:137], v[36:39]
	v_mfma_f32_16x16x32_bf16 v[24:27], v[142:145], v[134:137], v[24:27]
	s_nop 7
	s_nop 1
	ds_write_b128 v70, v[36:39]
	ds_write_b128 v70, v[24:27] offset:1024
	s_waitcnt lgkmcnt(0)
	s_waitcnt lgkmcnt(0)
	s_barrier
	ds_read_b128 v[98:101], v79
	ds_read_b128 v[102:105], v79 offset:1024
	ds_read_b128 v[106:109], v79 offset:16384
	ds_read_b128 v[110:113], v79 offset:17408
	ds_read_b128 v[114:117], v79 offset:32768
	ds_read_b128 v[118:121], v79 offset:33792
	ds_read_b128 v[122:125], v79 offset:49152
	ds_read_b128 v[126:129], v79 offset:50176
	ds_read_b128 v[130:133], v80
	ds_read_b128 v[134:137], v81
	ds_read_b128 v[138:141], v82
	ds_read_b128 v[142:145], v83
	ds_read_b128 v[146:149], v84
	ds_read_b128 v[150:153], v85
	ds_read_b128 v[154:157], v86
	ds_read_b128 v[0:3], v87
	s_waitcnt lgkmcnt(0)
	v_lshl_or_b32 v12, s7, 5, v88
	v_ashrrev_i32_e32 v13, 31, v12
	v_lshl_add_u64 v[14:15], v[12:13], 2, v[68:69]
	v_pk_add_f32 v[4:5], v[100:101], 0 op_sel_hi:[1,0]
	v_pk_add_f32 v[6:7], v[98:99], 0 op_sel_hi:[1,0]
	v_pk_add_f32 v[8:9], v[104:105], 0 op_sel_hi:[1,0]
	v_pk_add_f32 v[10:11], v[102:103], 0 op_sel_hi:[1,0]
	v_pk_add_f32 v[4:5], v[4:5], v[108:109]
	v_pk_add_f32 v[6:7], v[6:7], v[106:107]
	v_pk_add_f32 v[8:9], v[8:9], v[112:113]
	v_pk_add_f32 v[10:11], v[10:11], v[110:111]
	v_pk_add_f32 v[4:5], v[4:5], v[116:117]
	v_pk_add_f32 v[6:7], v[6:7], v[114:115]
	v_pk_add_f32 v[8:9], v[8:9], v[120:121]
	v_pk_add_f32 v[10:11], v[10:11], v[118:119]
	v_pk_add_f32 v[4:5], v[4:5], v[124:125]
	v_pk_add_f32 v[6:7], v[6:7], v[122:123]
	v_pk_add_f32 v[8:9], v[8:9], v[128:129]
	v_pk_add_f32 v[10:11], v[10:11], v[126:127]
	v_pk_add_f32 v[4:5], v[4:5], v[132:133]
	v_pk_add_f32 v[6:7], v[6:7], v[130:131]
	v_pk_add_f32 v[8:9], v[8:9], v[136:137]
	v_pk_add_f32 v[10:11], v[10:11], v[134:135]
	v_pk_add_f32 v[4:5], v[4:5], v[140:141]
	v_pk_add_f32 v[6:7], v[6:7], v[138:139]
	v_pk_add_f32 v[8:9], v[8:9], v[144:145]
	v_pk_add_f32 v[10:11], v[10:11], v[142:143]
	v_pk_add_f32 v[4:5], v[4:5], v[148:149]
	v_pk_add_f32 v[6:7], v[6:7], v[146:147]
	v_pk_add_f32 v[8:9], v[8:9], v[152:153]
	v_pk_add_f32 v[10:11], v[10:11], v[150:151]
	v_pk_add_f32 v[4:5], v[4:5], v[156:157]
	v_pk_add_f32 v[6:7], v[6:7], v[154:155]
	s_waitcnt lgkmcnt(0)
	s_waitcnt lgkmcnt(0)
	s_barrier
	s_mul_i32 exec_lo, s32, -1
	s_mov_b32 exec_hi, exec_lo
	v_pk_add_f32 v[8:9], v[8:9], v[2:3]
	v_pk_add_f32 v[10:11], v[10:11], v[0:1]
	global_load_dwordx4 v[0:3], v[14:15], off
	global_load_dwordx4 v[162:165], v[14:15], off offset:64
	s_waitcnt vmcnt(0)
	v_pk_add_f32 v[0:1], v[6:7], v[0:1]
	v_pk_add_f32 v[2:3], v[4:5], v[2:3]
	v_cvt_pk_bf16_f32 v4, v0, v1
	v_mul_f32_e32 v1, v1, v1
	v_lshl_add_u64 v[6:7], v[12:13], 1, v[64:65]
	v_fmac_f32_e32 v1, v0, v0
	v_mul_f32_e32 v0, v3, v3
	v_cvt_pk_bf16_f32 v5, v2, v3
	global_store_dwordx2 v[6:7], v[4:5], off
	v_fmac_f32_e32 v0, v2, v2
	v_add_f32_e32 v12, v1, v0
	s_waitcnt vmcnt(0)
	v_pk_add_f32 v[0:1], v[10:11], v[162:163]
	v_pk_add_f32 v[2:3], v[8:9], v[164:165]
	v_cvt_pk_bf16_f32 v4, v0, v1
	v_mul_f32_e32 v1, v1, v1
	v_fmac_f32_e32 v1, v0, v0
	v_mul_f32_e32 v0, v3, v3
	v_cvt_pk_bf16_f32 v5, v2, v3
	v_fmac_f32_e32 v0, v2, v2
	v_and_b32_e32 v2, 64, v225
	v_add_f32_e32 v0, v1, v0
	v_xor_b32_e32 v1, 16, v225
	v_add_u32_e32 v2, 64, v2
	v_cmp_lt_i32_e64 s[0:1], v1, v2
	v_add_f32_e32 v0, v12, v0
	global_store_dwordx2 v[6:7], v[4:5], off offset:32
	v_cndmask_b32_e64 v1, v225, v1, s[0:1]
	v_lshlrev_b32_e32 v1, 2, v1
	ds_bpermute_b32 v1, v1, v0
	s_waitcnt lgkmcnt(0)
	v_add_f32_e32 v0, v0, v1
	v_xor_b32_e32 v1, 32, v225
	v_cmp_lt_i32_e64 s[0:1], v1, v2
	s_nop 1
	v_cndmask_b32_e64 v1, v225, v1, s[0:1]
	v_lshlrev_b32_e32 v1, 2, v1
	ds_bpermute_b32 v1, v1, v0
	s_and_saveexec_b64 s[0:1], vcc
	s_cbranch_execz .LBB0_906
	s_waitcnt lgkmcnt(0)
	v_add_f32_e32 v0, v0, v1
	global_atomic_add_f32 v[66:67], v0, off
	s_branch .LBB0_906

; #define LAS __attribute__((address_space(3)))
; template <int KSTEPS  >
; __device__ __forceinline__ void small_mma_ksplit(f32x4 (&acc)[2], const bf16_t* A, int lda, const bf16_t* Bt, int ldb, int n0, LAS unsigned char* lds, const SmallId& id) {
;     ...
;     for (int ks = 0; ks < KSTEPS; ++ks) {
;         bf16x8 a[8], b[2];
; #pragma unroll
;         for (int rb = 0; rb < 8; ++rb) a[rb] = *(const bf16x8*)(ap + (size_t)(16 * rb) * lda + 32 * ks);
;         b[0] = *(const bf16x8*)(bp + 32 * ks); b[1] = *(const bf16x8*)(bp + (size_t)16 * ldb + 32 * ks);
; #pragma unroll
;         for (int rb = 0; rb < 8; ++rb) { part[rb][0] = __builtin_amdgcn_mfma_f32_16x16x32_bf16(b[0], a[rb], part[rb][0], 0, 0, 0); part[rb][1] = __builtin_amdgcn_mfma_f32_16x16x32_bf16(b[1], a[rb], part[rb][1], 0, 0, 0); }
;     }
;     LAS f32x4* red = (LAS f32x4*)lds;
; #pragma unroll
;     for (int rb = 0; rb < 8; ++rb) { red[((id.w * 8 + rb) * 2 + 0) * 64 + lane] = part[rb][0]; red[((id.w * 8 + rb) * 2 + 1) * 64 + lane] = part[rb][1]; }
;     asm volatile("s_waitcnt lgkmcnt(0)" ::: "memory"); __syncthreads();
.LBB0_1223:
	s_waitcnt lgkmcnt(0)
	v_readlane_b32 s0, v246, 8
	v_readfirstlane_b32 s32, v222
	s_bfe_u32 s0, s0, 0x30003
	s_lshr_b32 s32, s32, 6
	s_cmp_eq_u32 s32, s0
	s_cselect_b32 s32, 1, 0
	s_lshl_b32 s1, s0, 11
	v_add_u32_e32 v68, s1, v74
	s_sub_i32 s1, s53, s52
	s_mul_i32 s0, s0, s1
	s_add_i32 s0, s0, s52
	s_mov_b32 s1, 0
	v_lshl_add_u64 v[86:87], v[70:71], 0, s[0:1]
	s_mov_b32 s0, s62
	v_lshl_add_u64 v[88:89], v[72:73], 0, s[0:1]
	s_mov_b32 s0, s63
	v_lshl_add_u64 v[90:91], v[72:73], 0, s[0:1]
	global_load_dwordx4 v[92:95], v[86:87], off
	global_load_dwordx4 v[98:101], v[88:89], off
	global_load_dwordx4 v[102:105], v[90:91], off
	global_load_dwordx4 v[106:109], v[86:87], off offset:64
	global_load_dwordx4 v[110:113], v[88:89], off offset:64
	global_load_dwordx4 v[114:117], v[90:91], off offset:64
	global_load_dwordx4 v[118:121], v[86:87], off offset:128
	global_load_dwordx4 v[122:125], v[88:89], off offset:128
	global_load_dwordx4 v[126:129], v[90:91], off offset:128
	global_load_dwordx4 v[130:133], v[86:87], off offset:192
	global_load_dwordx4 v[134:137], v[88:89], off offset:192
	global_load_dwordx4 v[138:141], v[90:91], off offset:192
	global_load_dwordx4 v[142:145], v[86:87], off offset:256
	global_load_dwordx4 v[146:149], v[88:89], off offset:256
	global_load_dwordx4 v[150:153], v[90:91], off offset:256
	global_load_dwordx4 v[154:157], v[86:87], off offset:320
	global_load_dwordx4 v[158:161], v[88:89], off offset:320
	global_load_dwordx4 v[162:165], v[90:91], off offset:320
	global_load_dwordx4 v[166:169], v[86:87], off offset:384
	global_load_dwordx4 v[170:173], v[88:89], off offset:384
	global_load_dwordx4 v[174:177], v[90:91], off offset:384
	global_load_dwordx4 v[178:181], v[86:87], off offset:448
	global_load_dwordx4 v[182:185], v[88:89], off offset:448
	global_load_dwordx4 v[186:189], v[90:91], off offset:448
	s_waitcnt vmcnt(21)
	v_mfma_f32_16x16x32_bf16 v[36:39], v[98:101], v[92:95], v[36:39]
	v_mfma_f32_16x16x32_bf16 v[24:27], v[102:105], v[92:95], v[24:27]
	global_load_dwordx4 v[92:95], v[86:87], off offset:512
	global_load_dwordx4 v[98:101], v[88:89], off offset:512
	global_load_dwordx4 v[102:105], v[90:91], off offset:512
	s_waitcnt vmcnt(21)
	v_mfma_f32_16x16x32_bf16 v[36:39], v[110:113], v[106:109], v[36:39]
	v_mfma_f32_16x16x32_bf16 v[24:27], v[114:117], v[106:109], v[24:27]
	global_load_dwordx4 v[106:109], v[86:87], off offset:576
	global_load_dwordx4 v[110:113], v[88:89], off offset:576
	global_load_dwordx4 v[114:117], v[90:91], off offset:576
	s_waitcnt vmcnt(21)
	v_mfma_f32_16x16x32_bf16 v[36:39], v[122:125], v[118:121], v[36:39]
	v_mfma_f32_16x16x32_bf16 v[24:27], v[126:129], v[118:121], v[24:27]
	global_load_dwordx4 v[118:121], v[86:87], off offset:640
	global_load_dwordx4 v[122:125], v[88:89], off offset:640
	global_load_dwordx4 v[126:129], v[90:91], off offset:640
	s_waitcnt vmcnt(21)
	v_mfma_f32_16x16x32_bf16 v[36:39], v[134:137], v[130:133], v[36:39]
	v_mfma_f32_16x16x32_bf16 v[24:27], v[138:141], v[130:133], v[24:27]
	s_waitcnt vmcnt(18)
	v_mfma_f32_16x16x32_bf16 v[36:39], v[146:149], v[142:145], v[36:39]
	v_mfma_f32_16x16x32_bf16 v[24:27], v[150:153], v[142:145], v[24:27]
	s_waitcnt vmcnt(15)
	v_mfma_f32_16x16x32_bf16 v[36:39], v[158:161], v[154:157], v[36:39]
	v_mfma_f32_16x16x32_bf16 v[24:27], v[162:165], v[154:157], v[24:27]
	s_waitcnt vmcnt(12)
	v_mfma_f32_16x16x32_bf16 v[36:39], v[170:173], v[166:169], v[36:39]
	v_mfma_f32_16x16x32_bf16 v[24:27], v[174:177], v[166:169], v[24:27]
	s_waitcnt vmcnt(9)
	v_mfma_f32_16x16x32_bf16 v[36:39], v[182:185], v[178:181], v[36:39]
	v_mfma_f32_16x16x32_bf16 v[24:27], v[186:189], v[178:181], v[24:27]
	s_waitcnt vmcnt(6)
	v_mfma_f32_16x16x32_bf16 v[36:39], v[98:101], v[92:95], v[36:39]
	v_mfma_f32_16x16x32_bf16 v[24:27], v[102:105], v[92:95], v[24:27]
	s_waitcnt vmcnt(3)
	v_mfma_f32_16x16x32_bf16 v[36:39], v[110:113], v[106:109], v[36:39]
	v_mfma_f32_16x16x32_bf16 v[24:27], v[114:117], v[106:109], v[24:27]
	s_waitcnt vmcnt(0)
	v_mfma_f32_16x16x32_bf16 v[36:39], v[122:125], v[118:121], v[36:39]
	v_mfma_f32_16x16x32_bf16 v[24:27], v[126:129], v[118:121], v[24:27]
	s_nop 7
	s_nop 1
	ds_write_b128 v68, v[36:39]
	ds_write_b128 v68, v[24:27] offset:1024
	s_waitcnt lgkmcnt(0)
	s_waitcnt lgkmcnt(0)
	s_barrier
; __device__ __forceinline__ unsigned cvt_pk_bf16(float lo, float hi) { unsigned r; asm volatile("v_cvt_pk_bf16_f32 %0, %1, %2" : "=v"(r) : "v"(lo), "v"(hi)); return r; }
; template <int KSTEPS  >
; __device__ __forceinline__ void small_mma_ksplit(f32x4 (&acc)[2], const bf16_t* A, int lda, const bf16_t* Bt, int ldb, int n0, LAS unsigned char* lds, const SmallId& id) {
;     ...
;     acc[0] = (f32x4){0.f, 0.f, 0.f, 0.f}; acc[1] = acc[0];
; #pragma unroll
;     for (int w2 = 0; w2 < 8; ++w2) { acc[0] += red[((w2 * 8 + id.w) * 2 + 0) * 64 + lane]; acc[1] += red[((w2 * 8 + id.w) * 2 + 1) * 64 + lane]; }
;     asm volatile("s_waitcnt lgkmcnt(0)" ::: "memory"); __syncthreads();
; template <bool RES_F32, bool OUT_F32, int KSTEPS>
; __device__ __forceinline__ void small_res(const Params& p, LAS unsigned char* lds, const bf16_t* A, int lda, const bf16_t* Bt, int K, float* ssq_next, int G, int bx) {
;     ...
;         float s = 0.f;
; #pragma unroll
;         for (int nb = 0; nb < 2; ++nb) { const int col = n0 + 16 * nb + 4 * id.fq;
;             f32x4 r;
;             if (RES_F32) r = *(const f32x4*)(p.xs + (size_t)(id.row - MP) * DM + col);
;             else { const u32x2 w = *(const u32x2*)(XB + (size_t)id.row * DM + col); r = (f32x4){bf_lo(w.x), bf_hi(w.x), bf_lo(w.y), bf_hi(w.y)}; }
;             const f32x4 x = r + acc[nb];
;             if (OUT_F32) *(f32x4*)(p.out + (size_t)id.row * DM + col) = x;
;             else { u32x2 w; w.x = cvt_pk_bf16(x[0], x[1]); w.y = cvt_pk_bf16(x[2], x[3]); *(u32x2*)(XB + (size_t)id.row * DM + col) = w; }
;             s += (x[0] * x[0] + x[1] * x[1]) + (x[2] * x[2] + x[3] * x[3]); }
	ds_read_b128 v[92:95], v75
	ds_read_b128 v[98:101], v75 offset:1024
	ds_read_b128 v[102:105], v75 offset:16384
	ds_read_b128 v[106:109], v75 offset:17408
	ds_read_b128 v[110:113], v75 offset:32768
	ds_read_b128 v[114:117], v75 offset:33792
	ds_read_b128 v[118:121], v75 offset:49152
	ds_read_b128 v[122:125], v75 offset:50176
	ds_read_b128 v[126:129], v76
	ds_read_b128 v[130:133], v77
	ds_read_b128 v[134:137], v78
	ds_read_b128 v[138:141], v79
	ds_read_b128 v[142:145], v80
	ds_read_b128 v[146:149], v81
	ds_read_b128 v[150:153], v82
	ds_read_b128 v[0:3], v83
	s_waitcnt lgkmcnt(0)
	v_lshl_or_b32 v12, s2, 5, v84
	v_ashrrev_i32_e32 v13, 31, v12
	v_lshl_add_u64 v[14:15], v[12:13], 1, v[64:65]
	s_add_i32 s2, s2, s92
	v_pk_add_f32 v[4:5], v[94:95], 0 op_sel_hi:[1,0]
	v_pk_add_f32 v[6:7], v[92:93], 0 op_sel_hi:[1,0]
	v_add_u32_e32 v85, s37, v85
	s_cmp_lt_i32 s2, 32
	v_pk_add_f32 v[8:9], v[100:101], 0 op_sel_hi:[1,0]
	v_pk_add_f32 v[10:11], v[98:99], 0 op_sel_hi:[1,0]
	v_pk_add_f32 v[4:5], v[4:5], v[104:105]
	v_pk_add_f32 v[6:7], v[6:7], v[102:103]
	v_pk_add_f32 v[8:9], v[8:9], v[108:109]
	v_pk_add_f32 v[10:11], v[10:11], v[106:107]
	v_pk_add_f32 v[4:5], v[4:5], v[112:113]
	v_pk_add_f32 v[6:7], v[6:7], v[110:111]
	v_pk_add_f32 v[8:9], v[8:9], v[116:117]
	v_pk_add_f32 v[10:11], v[10:11], v[114:115]
	v_pk_add_f32 v[4:5], v[4:5], v[120:121]
	v_pk_add_f32 v[6:7], v[6:7], v[118:119]
	v_pk_add_f32 v[8:9], v[8:9], v[124:125]
	v_pk_add_f32 v[10:11], v[10:11], v[122:123]
	v_pk_add_f32 v[4:5], v[4:5], v[128:129]
	v_pk_add_f32 v[6:7], v[6:7], v[126:127]
	v_pk_add_f32 v[8:9], v[8:9], v[132:133]
	v_pk_add_f32 v[10:11], v[10:11], v[130:131]
	v_pk_add_f32 v[4:5], v[4:5], v[136:137]
	v_pk_add_f32 v[6:7], v[6:7], v[134:135]
	v_pk_add_f32 v[8:9], v[8:9], v[140:141]
	v_pk_add_f32 v[10:11], v[10:11], v[138:139]
	v_pk_add_f32 v[4:5], v[4:5], v[144:145]
	v_pk_add_f32 v[6:7], v[6:7], v[142:143]
	v_pk_add_f32 v[8:9], v[8:9], v[148:149]
	v_pk_add_f32 v[10:11], v[10:11], v[146:147]
	v_pk_add_f32 v[4:5], v[4:5], v[152:153]
	v_pk_add_f32 v[6:7], v[6:7], v[150:151]
	s_waitcnt lgkmcnt(0)
	s_waitcnt lgkmcnt(0)
	s_barrier
	s_mul_i32 exec_lo, s32, -1
	s_mov_b32 exec_hi, exec_lo
	v_pk_add_f32 v[10:11], v[10:11], v[0:1]
	global_load_dwordx2 v[0:1], v[14:15], off
	global_load_dwordx2 v[158:159], v[14:15], off offset:32
	v_pk_add_f32 v[8:9], v[8:9], v[2:3]
	s_waitcnt vmcnt(0) lgkmcnt(0)
	v_lshlrev_b32_e32 v2, 16, v0
	v_and_b32_e32 v3, 0xffff0000, v0
	v_lshlrev_b32_e32 v16, 16, v1
	v_and_b32_e32 v17, 0xffff0000, v1
	v_pk_add_f32 v[0:1], v[6:7], v[2:3]
	v_pk_add_f32 v[2:3], v[4:5], v[16:17]
	v_lshl_add_u64 v[4:5], v[12:13], 2, v[66:67]
	global_store_dwordx4 v[4:5], v[0:3], off
	s_waitcnt vmcnt(0) lgkmcnt(0)
	v_lshlrev_b32_e32 v6, 16, v158
	v_and_b32_e32 v7, 0xffff0000, v158
	v_lshlrev_b32_e32 v0, 16, v159
	v_and_b32_e32 v1, 0xffff0000, v159
	v_pk_add_f32 v[2:3], v[8:9], v[0:1]
	v_pk_add_f32 v[0:1], v[10:11], v[6:7]
	global_store_dwordx4 v[4:5], v[0:3], off offset:64
	s_cbranch_scc1 .LBB0_1222

; #define LAS __attribute__((address_space(3)))
; template <int KSTEPS  >
; __device__ __forceinline__ void small_mma_ksplit(f32x4 (&acc)[2], const bf16_t* A, int lda, const bf16_t* Bt, int ldb, int n0, LAS unsigned char* lds, const SmallId& id) {
;     ...
;     for (int ks = 0; ks < KSTEPS; ++ks) {
;         bf16x8 a[8], b[2];
; #pragma unroll
;         for (int rb = 0; rb < 8; ++rb) a[rb] = *(const bf16x8*)(ap + (size_t)(16 * rb) * lda + 32 * ks);
;         b[0] = *(const bf16x8*)(bp + 32 * ks); b[1] = *(const bf16x8*)(bp + (size_t)16 * ldb + 32 * ks);
; #pragma unroll
;         for (int rb = 0; rb < 8; ++rb) { part[rb][0] = __builtin_amdgcn_mfma_f32_16x16x32_bf16(b[0], a[rb], part[rb][0], 0, 0, 0); part[rb][1] = __builtin_amdgcn_mfma_f32_16x16x32_bf16(b[1], a[rb], part[rb][1], 0, 0, 0); }
;     }
;     LAS f32x4* red = (LAS f32x4*)lds;
; #pragma unroll
;     for (int rb = 0; rb < 8; ++rb) { red[((id.w * 8 + rb) * 2 + 0) * 64 + lane] = part[rb][0]; red[((id.w * 8 + rb) * 2 + 1) * 64 + lane] = part[rb][1]; }
;     asm volatile("s_waitcnt lgkmcnt(0)" ::: "memory"); __syncthreads();
.LBB0_1255:
	s_waitcnt lgkmcnt(0)
	v_readlane_b32 s8, v246, 8
	v_readfirstlane_b32 s32, v222
	s_bfe_u32 s8, s8, 0x30003
	s_lshr_b32 s32, s32, 6
	s_cmp_eq_u32 s32, s8
	s_cselect_b32 s32, 1, 0
	s_lshl_b32 s9, s8, 11
	v_add_u32_e32 v68, s9, v74
	s_sub_i32 s9, s53, s52
	s_mul_i32 s8, s8, s9
	s_add_i32 s8, s8, s52
	s_mov_b32 s9, 0
	v_lshl_add_u64 v[86:87], v[70:71], 0, s[8:9]
	s_mov_b32 s8, s62
	v_lshl_add_u64 v[88:89], v[72:73], 0, s[8:9]
	s_mov_b32 s8, s63
	v_lshl_add_u64 v[90:91], v[72:73], 0, s[8:9]
	global_load_dwordx4 v[92:95], v[86:87], off
	global_load_dwordx4 v[98:101], v[88:89], off
	global_load_dwordx4 v[102:105], v[90:91], off
	global_load_dwordx4 v[106:109], v[86:87], off offset:64
	global_load_dwordx4 v[110:113], v[88:89], off offset:64
	global_load_dwordx4 v[114:117], v[90:91], off offset:64
	global_load_dwordx4 v[118:121], v[86:87], off offset:128
	global_load_dwordx4 v[122:125], v[88:89], off offset:128
	global_load_dwordx4 v[126:129], v[90:91], off offset:128
	global_load_dwordx4 v[130:133], v[86:87], off offset:192
	global_load_dwordx4 v[134:137], v[88:89], off offset:192
	global_load_dwordx4 v[138:141], v[90:91], off offset:192
	global_load_dwordx4 v[142:145], v[86:87], off offset:256
	global_load_dwordx4 v[146:149], v[88:89], off offset:256
	global_load_dwordx4 v[150:153], v[90:91], off offset:256
	global_load_dwordx4 v[154:157], v[86:87], off offset:320
	global_load_dwordx4 v[158:161], v[88:89], off offset:320
	global_load_dwordx4 v[162:165], v[90:91], off offset:320
	global_load_dwordx4 v[166:169], v[86:87], off offset:384
	global_load_dwordx4 v[170:173], v[88:89], off offset:384
	global_load_dwordx4 v[174:177], v[90:91], off offset:384
	global_load_dwordx4 v[178:181], v[86:87], off offset:448
	global_load_dwordx4 v[182:185], v[88:89], off offset:448
	global_load_dwordx4 v[186:189], v[90:91], off offset:448
	s_waitcnt vmcnt(21)
	v_mfma_f32_16x16x32_bf16 v[36:39], v[98:101], v[92:95], v[36:39]
	v_mfma_f32_16x16x32_bf16 v[24:27], v[102:105], v[92:95], v[24:27]
	global_load_dwordx4 v[92:95], v[86:87], off offset:512
	global_load_dwordx4 v[98:101], v[88:89], off offset:512
	global_load_dwordx4 v[102:105], v[90:91], off offset:512
	s_waitcnt vmcnt(21)
	v_mfma_f32_16x16x32_bf16 v[36:39], v[110:113], v[106:109], v[36:39]
	v_mfma_f32_16x16x32_bf16 v[24:27], v[114:117], v[106:109], v[24:27]
	global_load_dwordx4 v[106:109], v[86:87], off offset:576
	global_load_dwordx4 v[110:113], v[88:89], off offset:576
	global_load_dwordx4 v[114:117], v[90:91], off offset:576
	s_waitcnt vmcnt(21)
	v_mfma_f32_16x16x32_bf16 v[36:39], v[122:125], v[118:121], v[36:39]
	v_mfma_f32_16x16x32_bf16 v[24:27], v[126:129], v[118:121], v[24:27]
	global_load_dwordx4 v[118:121], v[86:87], off offset:640
	global_load_dwordx4 v[122:125], v[88:89], off offset:640
	global_load_dwordx4 v[126:129], v[90:91], off offset:640
	s_waitcnt vmcnt(21)
	v_mfma_f32_16x16x32_bf16 v[36:39], v[134:137], v[130:133], v[36:39]
	v_mfma_f32_16x16x32_bf16 v[24:27], v[138:141], v[130:133], v[24:27]
	s_waitcnt vmcnt(18)
	v_mfma_f32_16x16x32_bf16 v[36:39], v[146:149], v[142:145], v[36:39]
	v_mfma_f32_16x16x32_bf16 v[24:27], v[150:153], v[142:145], v[24:27]
	s_waitcnt vmcnt(15)
	v_mfma_f32_16x16x32_bf16 v[36:39], v[158:161], v[154:157], v[36:39]
	v_mfma_f32_16x16x32_bf16 v[24:27], v[162:165], v[154:157], v[24:27]
	s_waitcnt vmcnt(12)
	v_mfma_f32_16x16x32_bf16 v[36:39], v[170:173], v[166:169], v[36:39]
	v_mfma_f32_16x16x32_bf16 v[24:27], v[174:177], v[166:169], v[24:27]
	s_waitcnt vmcnt(9)
	v_mfma_f32_16x16x32_bf16 v[36:39], v[182:185], v[178:181], v[36:39]
	v_mfma_f32_16x16x32_bf16 v[24:27], v[186:189], v[178:181], v[24:27]
	s_waitcnt vmcnt(6)
	v_mfma_f32_16x16x32_bf16 v[36:39], v[98:101], v[92:95], v[36:39]
	v_mfma_f32_16x16x32_bf16 v[24:27], v[102:105], v[92:95], v[24:27]
	s_waitcnt vmcnt(3)
	v_mfma_f32_16x16x32_bf16 v[36:39], v[110:113], v[106:109], v[36:39]
	v_mfma_f32_16x16x32_bf16 v[24:27], v[114:117], v[106:109], v[24:27]
	s_waitcnt vmcnt(0)
	v_mfma_f32_16x16x32_bf16 v[36:39], v[122:125], v[118:121], v[36:39]
	v_mfma_f32_16x16x32_bf16 v[24:27], v[126:129], v[118:121], v[24:27]
	s_nop 7
	s_nop 1
	ds_write_b128 v68, v[36:39]
	ds_write_b128 v68, v[24:27] offset:1024
	s_waitcnt lgkmcnt(0)
	s_waitcnt lgkmcnt(0)
	s_barrier
; __device__ __forceinline__ unsigned cvt_pk_bf16(float lo, float hi) { unsigned r; asm volatile("v_cvt_pk_bf16_f32 %0, %1, %2" : "=v"(r) : "v"(lo), "v"(hi)); return r; }
; template <int KSTEPS  >
; __device__ __forceinline__ void small_mma_ksplit(f32x4 (&acc)[2], const bf16_t* A, int lda, const bf16_t* Bt, int ldb, int n0, LAS unsigned char* lds, const SmallId& id) {
;     ...
;     acc[0] = (f32x4){0.f, 0.f, 0.f, 0.f}; acc[1] = acc[0];
; #pragma unroll
;     for (int w2 = 0; w2 < 8; ++w2) { acc[0] += red[((w2 * 8 + id.w) * 2 + 0) * 64 + lane]; acc[1] += red[((w2 * 8 + id.w) * 2 + 1) * 64 + lane]; }
;     asm volatile("s_waitcnt lgkmcnt(0)" ::: "memory"); __syncthreads();
; template <bool RES_F32, bool OUT_F32, int KSTEPS>
; __device__ __forceinline__ void small_res(const Params& p, LAS unsigned char* lds, const bf16_t* A, int lda, const bf16_t* Bt, int K, float* ssq_next, int G, int bx) {
;     ...
;         float s = 0.f;
; #pragma unroll
;         for (int nb = 0; nb < 2; ++nb) { const int col = n0 + 16 * nb + 4 * id.fq;
;             f32x4 r;
;             if (RES_F32) r = *(const f32x4*)(p.xs + (size_t)(id.row - MP) * DM + col);
;             else { const u32x2 w = *(const u32x2*)(XB + (size_t)id.row * DM + col); r = (f32x4){bf_lo(w.x), bf_hi(w.x), bf_lo(w.y), bf_hi(w.y)}; }
;             const f32x4 x = r + acc[nb];
;             if (OUT_F32) *(f32x4*)(p.out + (size_t)id.row * DM + col) = x;
;             else { u32x2 w; w.x = cvt_pk_bf16(x[0], x[1]); w.y = cvt_pk_bf16(x[2], x[3]); *(u32x2*)(XB + (size_t)id.row * DM + col) = w; }
;             s += (x[0] * x[0] + x[1] * x[1]) + (x[2] * x[2] + x[3] * x[3]); }
;         if (!OUT_F32) { s += __shfl_xor(s, 16); s += __shfl_xor(s, 32); if (id.fq == 0) atomicAdd(ssq_next + id.row, s); }
;     }
	ds_read_b128 v[92:95], v75
	ds_read_b128 v[98:101], v75 offset:1024
	ds_read_b128 v[102:105], v75 offset:16384
	ds_read_b128 v[106:109], v75 offset:17408
	ds_read_b128 v[110:113], v75 offset:32768
	ds_read_b128 v[114:117], v75 offset:33792
	ds_read_b128 v[118:121], v75 offset:49152
	ds_read_b128 v[122:125], v75 offset:50176
	ds_read_b128 v[126:129], v76
	ds_read_b128 v[130:133], v77
	ds_read_b128 v[134:137], v78
	ds_read_b128 v[138:141], v79
	ds_read_b128 v[142:145], v80
	ds_read_b128 v[146:149], v81
	ds_read_b128 v[150:153], v82
	ds_read_b128 v[0:3], v83
	s_waitcnt lgkmcnt(0)
	v_pk_add_f32 v[4:5], v[94:95], 0 op_sel_hi:[1,0]
	v_pk_add_f32 v[6:7], v[92:93], 0 op_sel_hi:[1,0]
	v_pk_add_f32 v[8:9], v[100:101], 0 op_sel_hi:[1,0]
	v_pk_add_f32 v[10:11], v[98:99], 0 op_sel_hi:[1,0]
	v_pk_add_f32 v[4:5], v[4:5], v[104:105]
	v_pk_add_f32 v[6:7], v[6:7], v[102:103]
	v_pk_add_f32 v[8:9], v[8:9], v[108:109]
	v_pk_add_f32 v[10:11], v[10:11], v[106:107]
	v_pk_add_f32 v[4:5], v[4:5], v[112:113]
	v_pk_add_f32 v[6:7], v[6:7], v[110:111]
	v_pk_add_f32 v[8:9], v[8:9], v[116:117]
	v_pk_add_f32 v[10:11], v[10:11], v[114:115]
	v_pk_add_f32 v[4:5], v[4:5], v[120:121]
	v_pk_add_f32 v[6:7], v[6:7], v[118:119]
	v_pk_add_f32 v[8:9], v[8:9], v[124:125]
	v_pk_add_f32 v[10:11], v[10:11], v[122:123]
	v_pk_add_f32 v[4:5], v[4:5], v[128:129]
	v_pk_add_f32 v[6:7], v[6:7], v[126:127]
	v_pk_add_f32 v[8:9], v[8:9], v[132:133]
	v_pk_add_f32 v[10:11], v[10:11], v[130:131]
	v_pk_add_f32 v[4:5], v[4:5], v[136:137]
	v_pk_add_f32 v[6:7], v[6:7], v[134:135]
	v_pk_add_f32 v[8:9], v[8:9], v[140:141]
	v_pk_add_f32 v[10:11], v[10:11], v[138:139]
	v_pk_add_f32 v[4:5], v[4:5], v[144:145]
	v_pk_add_f32 v[6:7], v[6:7], v[142:143]
	v_pk_add_f32 v[8:9], v[8:9], v[148:149]
	v_pk_add_f32 v[10:11], v[10:11], v[146:147]
	v_pk_add_f32 v[4:5], v[4:5], v[152:153]
	v_pk_add_f32 v[6:7], v[6:7], v[150:151]
	s_waitcnt lgkmcnt(0)
	s_waitcnt lgkmcnt(0)
	s_barrier
	s_mul_i32 exec_lo, s32, -1
	s_mov_b32 exec_hi, exec_lo
	v_pk_add_f32 v[2:3], v[8:9], v[2:3]
	v_lshl_or_b32 v8, s7, 5, v84
	v_ashrrev_i32_e32 v9, 31, v8
	v_lshl_add_u64 v[8:9], v[8:9], 1, v[64:65]
	v_pk_add_f32 v[0:1], v[10:11], v[0:1]
	global_load_dwordx2 v[10:11], v[8:9], off
	global_load_dwordx2 v[158:159], v[8:9], off offset:32
	s_waitcnt vmcnt(0) lgkmcnt(0)
	v_lshlrev_b32_e32 v12, 16, v10
	v_and_b32_e32 v13, 0xffff0000, v10
	v_lshlrev_b32_e32 v10, 16, v11
	v_and_b32_e32 v11, 0xffff0000, v11
	v_pk_add_f32 v[4:5], v[4:5], v[10:11]
	v_pk_add_f32 v[6:7], v[6:7], v[12:13]
	s_nop 0
	v_cvt_pk_bf16_f32 v10, v6, v7
	v_cvt_pk_bf16_f32 v11, v4, v5
	v_mul_f32_e32 v7, v7, v7
	v_mul_f32_e32 v5, v5, v5
	v_fmac_f32_e32 v7, v6, v6
	v_fmac_f32_e32 v5, v4, v4
	global_store_dwordx2 v[8:9], v[10:11], off
	v_add_f32_e32 v10, v7, v5
	s_waitcnt vmcnt(0) lgkmcnt(0)
	v_lshlrev_b32_e32 v6, 16, v158
	v_and_b32_e32 v7, 0xffff0000, v158
	v_lshlrev_b32_e32 v4, 16, v159
	v_and_b32_e32 v5, 0xffff0000, v159
	v_pk_add_f32 v[0:1], v[0:1], v[6:7]
	v_pk_add_f32 v[2:3], v[2:3], v[4:5]
	v_cvt_pk_bf16_f32 v4, v0, v1
	v_mul_f32_e32 v1, v1, v1
	v_fmac_f32_e32 v1, v0, v0
	v_mul_f32_e32 v0, v3, v3
	v_cvt_pk_bf16_f32 v5, v2, v3
	v_fmac_f32_e32 v0, v2, v2
	v_and_b32_e32 v2, 64, v225
	v_add_f32_e32 v0, v1, v0
	v_xor_b32_e32 v1, 16, v225
	v_add_u32_e32 v2, 64, v2
	v_cmp_lt_i32_e64 s[0:1], v1, v2
	v_add_f32_e32 v0, v10, v0
	global_store_dwordx2 v[8:9], v[4:5], off offset:32
	v_cndmask_b32_e64 v1, v225, v1, s[0:1]
	v_lshlrev_b32_e32 v1, 2, v1
	ds_bpermute_b32 v1, v1, v0
	s_waitcnt lgkmcnt(0)
	v_add_f32_e32 v0, v0, v1
	v_xor_b32_e32 v1, 32, v225
	v_cmp_lt_i32_e64 s[0:1], v1, v2
	s_nop 1
	v_cndmask_b32_e64 v1, v225, v1, s[0:1]
	v_lshlrev_b32_e32 v1, 2, v1
	ds_bpermute_b32 v1, v1, v0
	s_and_saveexec_b64 s[0:1], vcc
	s_cbranch_execz .LBB0_1253
	s_waitcnt lgkmcnt(0)
	v_add_f32_e32 v0, v0, v1
	global_atomic_add_f32 v[66:67], v0, off
	s_branch .LBB0_1253
